# also the P6 sample_rows_gemm K loop: cooperative coalesced loads staged through padded LDS (same structure as the P9 one)
# speedup vs baseline: 1.0092x; 1.0032x over previous
; #define MFMA32(a, b, c) __builtin_amdgcn_mfma_f32_32x32x16_bf16(a, b, c, 0, 0, 0)
; template <int WHICH> __device__ __forceinline__ void sample_rows_gemm(const Params& P, const Ctx& C) {
;     ...
;     for (int pc = C.blk; pc < 256; pc += C.nblk) {
;         const int rb = pc >> 4, cb = pc & 15;
;         const int m = NPR + rb * 32 + r32;
;         const bf16_t* wp = WT + (size_t)(cb * 64 + r32) * K + wave * KE + 8 * hi; const bf16_t* ap = ACT + (size_t)m * K + wave * KE + 8 * hi;
;         f32x16 acc0 = F16Z_, acc1 = F16Z_;
; #pragma unroll (WHICH == 0 ? 8 : 11)
;         for (int ks = 0; ks < KE / 16; ++ks) { const bf16x8 af = *(const bf16x8*)(ap + 16 * ks);
;             acc0 = MFMA32(*(const bf16x8*)(wp + 16 * ks), af, acc0); acc1 = MFMA32(*(const bf16x8*)(wp + (size_t)32 * K + 16 * ks), af, acc1); }
.LBB0_1718:
	v_mbcnt_lo_u32_b32 v83, -1, 0
	v_mbcnt_hi_u32_b32 v83, -1, v83
	v_readlane_b32 vcc_hi, v254, 6
	v_lshrrev_b32_e32 v81, 4, v83
	v_and_b32_e32 v82, 15, v83
	v_mul_u32_u24_e32 v80, 2048, v81
	v_lshl_add_u32 v80, v82, 4, v80
	v_mul_u32_u24_e32 v81, 272, v81
	v_lshl_add_u32 v81, v82, 4, v81
	s_mul_i32 vcc_lo, vcc_hi, 3264
	v_add_u32_e32 v81, vcc_lo, v81
	v_and_b32_e32 v82, 31, v83
	v_mul_u32_u24_e32 v82, 272, v82
	v_lshrrev_b32_e32 v83, 5, v83
	v_lshl_add_u32 v82, v83, 4, v82
	s_lshl_b32 vcc_lo, vcc_hi, 5
	v_add_u32_e32 v82, vcc_lo, v82
	s_mul_i32 vcc_lo, vcc_hi, 12
	s_and_b32 s22, s20, 15
	s_lshl_b32 s22, s22, 6
	s_add_u32 s22, s22, vcc_lo
	s_mul_i32 s22, s22, 2048
	s_add_u32 s22, s22, 0x800000
	s_lshr_b32 s23, s20, 4
	s_lshl_b32 s23, s23, 5
	s_add_u32 s23, s23, vcc_lo
	s_addk_i32 s23, 16320
	s_mul_i32 s23, s23, 2048
	s_add_u32 s23, s23, 0x7d00000
	s_cmp_lt_u32 vcc_lo, 64
	s_cselect_b32 s22, s22, s23
	s_add_u32 s22, s14, s22
	s_addc_u32 s23, s15, 0
	s_mul_i32 vcc_lo, vcc_hi, 12
	s_add_u32 vcc_lo, vcc_lo, 4
	s_and_b32 s98, s20, 15
	s_lshl_b32 s98, s98, 6
	s_add_u32 s98, s98, vcc_lo
	s_mul_i32 s98, s98, 2048
	s_add_u32 s98, s98, 0x800000
	s_lshr_b32 s99, s20, 4
	s_lshl_b32 s99, s99, 5
	s_add_u32 s99, s99, vcc_lo
	s_addk_i32 s99, 16320
	s_mul_i32 s99, s99, 2048
	s_add_u32 s99, s99, 0x7d00000
	s_cmp_lt_u32 vcc_lo, 64
	s_cselect_b32 s98, s98, s99
	s_add_u32 s98, s14, s98
	s_addc_u32 s99, s15, 0
	s_mul_i32 vcc_lo, vcc_hi, 12
	s_add_u32 vcc_lo, vcc_lo, 8
	s_and_b32 s100, s20, 15
	s_lshl_b32 s100, s100, 6
	s_add_u32 s100, s100, vcc_lo
	s_mul_i32 s100, s100, 2048
	s_add_u32 s100, s100, 0x800000
	s_lshr_b32 s101, s20, 4
	s_lshl_b32 s101, s101, 5
	s_add_u32 s101, s101, vcc_lo
	s_addk_i32 s101, 16320
	s_mul_i32 s101, s101, 2048
	s_add_u32 s101, s101, 0x7d00000
	s_cmp_lt_u32 vcc_lo, 64
	s_cselect_b32 s100, s100, s101
	s_add_u32 s100, s14, s100
	s_addc_u32 s101, s15, 0
	s_barrier
	global_load_dwordx4 v[44:47], v80, s[22:23] offset:0
	global_load_dwordx4 v[48:51], v80, s[98:99] offset:0
	global_load_dwordx4 v[52:55], v80, s[100:101] offset:0
	global_load_dwordx4 v[56:59], v80, s[22:23] offset:256
	global_load_dwordx4 v[60:63], v80, s[98:99] offset:256
	global_load_dwordx4 v[64:67], v80, s[100:101] offset:256
	s_waitcnt vmcnt(3)
	ds_write_b128 v81, v[44:47] offset:0
	ds_write_b128 v81, v[48:51] offset:1088
	ds_write_b128 v81, v[52:55] offset:2176
	s_waitcnt lgkmcnt(0)
	s_barrier
	ds_read_b128 v[68:71], v82 offset:0
	ds_read_b128 v[76:79], v82 offset:17408
	ds_read_b128 v[72:75], v82 offset:8704
	global_load_dwordx4 v[44:47], v80, s[22:23] offset:512
	global_load_dwordx4 v[48:51], v80, s[98:99] offset:512
	global_load_dwordx4 v[52:55], v80, s[100:101] offset:512
	s_waitcnt lgkmcnt(1)
	v_mfma_f32_32x32x16_bf16 v[0:15], v[68:71], v[76:79], 0
	s_waitcnt lgkmcnt(0)
	v_mfma_f32_32x32x16_bf16 v[16:31], v[72:75], v[76:79], 0
	s_waitcnt vmcnt(3)
	ds_write_b128 v81, v[56:59] offset:26112
	ds_write_b128 v81, v[60:63] offset:27200
	ds_write_b128 v81, v[64:67] offset:28288
	s_waitcnt lgkmcnt(0)
	s_barrier
	ds_read_b128 v[68:71], v82 offset:26112
	ds_read_b128 v[76:79], v82 offset:43520
	ds_read_b128 v[72:75], v82 offset:34816
	global_load_dwordx4 v[56:59], v80, s[22:23] offset:768
	global_load_dwordx4 v[60:63], v80, s[98:99] offset:768
	global_load_dwordx4 v[64:67], v80, s[100:101] offset:768
	s_waitcnt lgkmcnt(1)
	v_mfma_f32_32x32x16_bf16 v[0:15], v[68:71], v[76:79], v[0:15]
	s_waitcnt lgkmcnt(0)
	v_mfma_f32_32x32x16_bf16 v[16:31], v[72:75], v[76:79], v[16:31]
	s_waitcnt vmcnt(3)
	ds_write_b128 v81, v[44:47] offset:0
	ds_write_b128 v81, v[48:51] offset:1088
	ds_write_b128 v81, v[52:55] offset:2176
	s_waitcnt lgkmcnt(0)
	s_barrier
	ds_read_b128 v[68:71], v82 offset:0
	ds_read_b128 v[76:79], v82 offset:17408
	ds_read_b128 v[72:75], v82 offset:8704
	global_load_dwordx4 v[44:47], v80, s[22:23] offset:1024
	global_load_dwordx4 v[48:51], v80, s[98:99] offset:1024
	global_load_dwordx4 v[52:55], v80, s[100:101] offset:1024
	s_waitcnt lgkmcnt(1)
	v_mfma_f32_32x32x16_bf16 v[0:15], v[68:71], v[76:79], v[0:15]
	s_waitcnt lgkmcnt(0)
	v_mfma_f32_32x32x16_bf16 v[16:31], v[72:75], v[76:79], v[16:31]
	s_waitcnt vmcnt(3)
	ds_write_b128 v81, v[56:59] offset:26112
	ds_write_b128 v81, v[60:63] offset:27200
	ds_write_b128 v81, v[64:67] offset:28288
	s_waitcnt lgkmcnt(0)
	s_barrier
	ds_read_b128 v[68:71], v82 offset:26112
	ds_read_b128 v[76:79], v82 offset:43520
	ds_read_b128 v[72:75], v82 offset:34816
	global_load_dwordx4 v[56:59], v80, s[22:23] offset:1280
	global_load_dwordx4 v[60:63], v80, s[98:99] offset:1280
	global_load_dwordx4 v[64:67], v80, s[100:101] offset:1280
	s_waitcnt lgkmcnt(1)
	v_mfma_f32_32x32x16_bf16 v[0:15], v[68:71], v[76:79], v[0:15]
	s_waitcnt lgkmcnt(0)
	v_mfma_f32_32x32x16_bf16 v[16:31], v[72:75], v[76:79], v[16:31]
	s_waitcnt vmcnt(3)
	ds_write_b128 v81, v[44:47] offset:0
	ds_write_b128 v81, v[48:51] offset:1088
	ds_write_b128 v81, v[52:55] offset:2176
	s_waitcnt lgkmcnt(0)
	s_barrier
	ds_read_b128 v[68:71], v82 offset:0
	ds_read_b128 v[76:79], v82 offset:17408
	ds_read_b128 v[72:75], v82 offset:8704
	global_load_dwordx4 v[44:47], v80, s[22:23] offset:1536
	global_load_dwordx4 v[48:51], v80, s[98:99] offset:1536
	global_load_dwordx4 v[52:55], v80, s[100:101] offset:1536
	s_waitcnt lgkmcnt(1)
	v_mfma_f32_32x32x16_bf16 v[0:15], v[68:71], v[76:79], v[0:15]
	s_waitcnt lgkmcnt(0)
	v_mfma_f32_32x32x16_bf16 v[16:31], v[72:75], v[76:79], v[16:31]
	s_waitcnt vmcnt(3)
	ds_write_b128 v81, v[56:59] offset:26112
	ds_write_b128 v81, v[60:63] offset:27200
	ds_write_b128 v81, v[64:67] offset:28288
	s_waitcnt lgkmcnt(0)
	s_barrier
; #define MFMA32(a, b, c) __builtin_amdgcn_mfma_f32_32x32x16_bf16(a, b, c, 0, 0, 0)
; template <int WHICH> __device__ __forceinline__ void sample_rows_gemm(const Params& P, const Ctx& C) {
;     ...
;         for (int ks = 0; ks < KE / 16; ++ks) { const bf16x8 af = *(const bf16x8*)(ap + 16 * ks);
;             acc0 = MFMA32(*(const bf16x8*)(wp + 16 * ks), af, acc0); acc1 = MFMA32(*(const bf16x8*)(wp + (size_t)32 * K + 16 * ks), af, acc1); }
;         __syncthreads();
; #pragma unroll
;         for (int r = 0; r < 16; ++r) { R[((wave * 2 + 0) * 16 + r) * 64 + lane] = acc0[r]; R[((wave * 2 + 1) * 16 + r) * 64 + lane] = acc1[r]; }
;         __syncthreads();
;         if (wave < 2) { const int nb = wave; f32x16 acc;
; #pragma unroll
;             for (int r = 0; r < 16; ++r) { float s = R[((0 * 2 + nb) * 16 + r) * 64 + lane];
; #pragma unroll
;                 for (int w8 = 1; w8 < 8; ++w8) s += R[((w8 * 2 + nb) * 16 + r) * 64 + lane];
;                 acc[r] = s; }
;             const float* MOD = (const float*)(ws + WS_MOD) + (size_t)pg8::mod_row(m) * 6144 + (WHICH == 0 ? 2048 : 5120);
;             const float* res = (WHICH == 0) ? P.in[1] + (size_t)(m - NPR) * DM : (const float*)(ws + WS_X1) + (size_t)m * DM;
;             float* dst = (WHICH == 0) ? (float*)(ws + WS_X1) + (size_t)m * DM : P.out + (size_t)m * DM;
; #pragma unroll
;             for (int rq = 0; rq < 4; ++rq) { const int c0 = cb * 64 + nb * 32 + 8 * rq + 4 * hi;
;                 const f32x4 a = {acc[4 * rq], acc[4 * rq + 1], acc[4 * rq + 2], acc[4 * rq + 3]};
;                 *(f32x4*)(dst + c0) = *(const f32x4*)(res + c0) + *(const f32x4*)(MOD + c0) * a; }
	ds_read_b128 v[68:71], v82 offset:26112
	ds_read_b128 v[76:79], v82 offset:43520
	ds_read_b128 v[72:75], v82 offset:34816
	global_load_dwordx4 v[56:59], v80, s[22:23] offset:1792
	global_load_dwordx4 v[60:63], v80, s[98:99] offset:1792
	global_load_dwordx4 v[64:67], v80, s[100:101] offset:1792
	s_waitcnt lgkmcnt(1)
	v_mfma_f32_32x32x16_bf16 v[0:15], v[68:71], v[76:79], v[0:15]
	s_waitcnt lgkmcnt(0)
	v_mfma_f32_32x32x16_bf16 v[16:31], v[72:75], v[76:79], v[16:31]
	s_waitcnt vmcnt(3)
	ds_write_b128 v81, v[44:47] offset:0
	ds_write_b128 v81, v[48:51] offset:1088
	ds_write_b128 v81, v[52:55] offset:2176
	s_waitcnt lgkmcnt(0)
	s_barrier
	ds_read_b128 v[68:71], v82 offset:0
	ds_read_b128 v[76:79], v82 offset:17408
	ds_read_b128 v[72:75], v82 offset:8704
	s_waitcnt lgkmcnt(1)
	v_mfma_f32_32x32x16_bf16 v[0:15], v[68:71], v[76:79], v[0:15]
	s_waitcnt lgkmcnt(0)
	v_mfma_f32_32x32x16_bf16 v[16:31], v[72:75], v[76:79], v[16:31]
	s_waitcnt vmcnt(0)
	ds_write_b128 v81, v[56:59] offset:26112
	ds_write_b128 v81, v[60:63] offset:27200
	ds_write_b128 v81, v[64:67] offset:28288
	s_waitcnt lgkmcnt(0)
	s_barrier
	ds_read_b128 v[68:71], v82 offset:26112
	ds_read_b128 v[76:79], v82 offset:43520
	ds_read_b128 v[72:75], v82 offset:34816
	s_waitcnt lgkmcnt(1)
	v_mfma_f32_32x32x16_bf16 v[0:15], v[68:71], v[76:79], v[0:15]
	s_waitcnt lgkmcnt(0)
	v_mfma_f32_32x32x16_bf16 v[16:31], v[72:75], v[76:79], v[16:31]
	s_and_b32 s21, s0, 0x3c0
	s_and_b32 s22, s10, 0xffffffe0
	s_addk_i32 s22, 0x4000
	v_or_b32_e32 v38, s22, v40
	v_ashrrev_i32_e32 v39, 31, v38
	s_and_b64 vcc, exec, s[2:3]
	s_waitcnt lgkmcnt(0)
	s_barrier
	s_nop 9
	ds_write2st64_b32 v43, v0, v1 offset1:1
	ds_write2st64_b32 v43, v2, v3 offset0:2 offset1:3
	ds_write2st64_b32 v43, v4, v5 offset0:4 offset1:5
	ds_write2st64_b32 v43, v6, v7 offset0:6 offset1:7
	ds_write2st64_b32 v43, v8, v9 offset0:8 offset1:9
	ds_write2st64_b32 v43, v10, v11 offset0:10 offset1:11
	ds_write2st64_b32 v43, v12, v13 offset0:12 offset1:13
	ds_write2st64_b32 v43, v14, v15 offset0:14 offset1:15
	ds_write2st64_b32 v43, v16, v17 offset0:16 offset1:17
	ds_write2st64_b32 v43, v18, v19 offset0:18 offset1:19
	ds_write2st64_b32 v43, v20, v21 offset0:20 offset1:21
	ds_write2st64_b32 v43, v22, v23 offset0:22 offset1:23
	ds_write2st64_b32 v43, v24, v25 offset0:24 offset1:25
	ds_write2st64_b32 v43, v26, v27 offset0:26 offset1:27
	ds_write2st64_b32 v43, v28, v29 offset0:28 offset1:29
	ds_write2st64_b32 v43, v30, v31 offset0:30 offset1:31
	s_waitcnt lgkmcnt(0)
	s_barrier
	s_cbranch_vccnz .LBB0_1717
	v_add_u32_e32 v0, 0xffffc000, v38
	s_ashr_i32 s22, s22, 13
	v_lshrrev_b32_e32 v1, 2, v0
	v_add_u32_e32 v1, 2, v1
	v_mov_b32_e32 v2, s22
	v_cmp_gt_i32_e32 vcc, s16, v38
	v_lshlrev_b64 v[12:13], 10, v[38:39]
	v_lshl_add_u64 v[12:13], v[12:13], 2, s[4:5]
	v_cndmask_b32_e32 v1, v1, v2, vcc
	v_mov_b64_e32 v[2:3], s[14:15]
	v_mad_i64_i32 v[4:5], s[22:23], v1, s18, v[2:3]
	v_add_u32_e32 v2, s21, v42
	v_ashrrev_i32_e32 v3, 31, v2
	v_ashrrev_i32_e32 v1, 31, v0
	v_lshlrev_b64 v[8:9], 2, v[2:3]
	v_lshlrev_b64 v[0:1], 12, v[0:1]
	v_lshl_add_u64 v[10:11], v[4:5], 0, v[8:9]
	v_lshl_add_u64 v[0:1], s[6:7], 0, v[0:1]
	v_add_co_u32_e32 v4, vcc, s19, v10
	v_lshl_add_u64 v[16:17], v[0:1], 0, v[8:9]
	s_nop 0
	v_addc_co_u32_e32 v5, vcc, 0, v11, vcc
	global_load_dwordx4 v[0:3], v[16:17], off
	v_lshl_add_u64 v[90:91], v[12:13], 0, v[8:9]
	global_load_dwordx4 v[4:7], v[4:5], off
	ds_read2st64_b32 v[14:15], v41 offset1:1
	ds_read2st64_b32 v[18:19], v41 offset0:2 offset1:3
	ds_read2st64_b32 v[20:21], v41 offset0:4 offset1:5
	ds_read2st64_b32 v[22:23], v41 offset0:6 offset1:7
	ds_read2st64_b32 v[24:25], v41 offset0:32 offset1:33
	ds_read2st64_b32 v[26:27], v41 offset0:34 offset1:35
	ds_read2st64_b32 v[28:29], v41 offset0:36 offset1:37
	ds_read2st64_b32 v[30:31], v41 offset0:38 offset1:39
	ds_read2st64_b32 v[38:39], v41 offset0:64 offset1:65
	ds_read2st64_b32 v[44:45], v41 offset0:66 offset1:67
	ds_read2st64_b32 v[46:47], v41 offset0:68 offset1:69
	ds_read2st64_b32 v[48:49], v41 offset0:70 offset1:71
	ds_read2st64_b32 v[50:51], v41 offset0:96 offset1:97
	ds_read2st64_b32 v[52:53], v41 offset0:98 offset1:99
	ds_read2st64_b32 v[54:55], v41 offset0:100 offset1:101
	ds_read2st64_b32 v[56:57], v41 offset0:102 offset1:103
	ds_read2st64_b32 v[58:59], v41 offset0:128 offset1:129
	ds_read2st64_b32 v[60:61], v41 offset0:130 offset1:131
	ds_read2st64_b32 v[62:63], v41 offset0:132 offset1:133
	ds_read2st64_b32 v[64:65], v41 offset0:134 offset1:135
	ds_read2st64_b32 v[66:67], v41 offset0:160 offset1:161
	ds_read2st64_b32 v[68:69], v41 offset0:162 offset1:163
	ds_read2st64_b32 v[70:71], v41 offset0:164 offset1:165
	ds_read2st64_b32 v[72:73], v41 offset0:166 offset1:167
	ds_read2st64_b32 v[74:75], v41 offset0:192 offset1:193
	ds_read2st64_b32 v[76:77], v41 offset0:194 offset1:195
	ds_read2st64_b32 v[78:79], v41 offset0:196 offset1:197
	ds_read2st64_b32 v[80:81], v41 offset0:198 offset1:199
	ds_read2st64_b32 v[82:83], v41 offset0:224 offset1:225
	ds_read2st64_b32 v[84:85], v41 offset0:226 offset1:227
	ds_read2st64_b32 v[86:87], v41 offset0:228 offset1:229
	ds_read2st64_b32 v[88:89], v41 offset0:230 offset1:231
	s_waitcnt lgkmcnt(14)
; template <int WHICH> __device__ __forceinline__ void sample_rows_gemm(const Params& P, const Ctx& C) {
;     ...
;         if (wave < 2) { const int nb = wave; f32x16 acc;
; #pragma unroll
;             for (int r = 0; r < 16; ++r) { float s = R[((0 * 2 + nb) * 16 + r) * 64 + lane];
; #pragma unroll
;                 for (int w8 = 1; w8 < 8; ++w8) s += R[((w8 * 2 + nb) * 16 + r) * 64 + lane];
;                 acc[r] = s; }
;             const float* MOD = (const float*)(ws + WS_MOD) + (size_t)pg8::mod_row(m) * 6144 + (WHICH == 0 ? 2048 : 5120);
;             const float* res = (WHICH == 0) ? P.in[1] + (size_t)(m - NPR) * DM : (const float*)(ws + WS_X1) + (size_t)m * DM;
;             float* dst = (WHICH == 0) ? (float*)(ws + WS_X1) + (size_t)m * DM : P.out + (size_t)m * DM;
; #pragma unroll
;             for (int rq = 0; rq < 4; ++rq) { const int c0 = cb * 64 + nb * 32 + 8 * rq + 4 * hi;
;                 const f32x4 a = {acc[4 * rq], acc[4 * rq + 1], acc[4 * rq + 2], acc[4 * rq + 3]};
;                 *(f32x4*)(dst + c0) = *(const f32x4*)(res + c0) + *(const f32x4*)(MOD + c0) * a; }
	v_pk_add_f32 v[8:9], v[14:15], v[24:25]
	v_pk_add_f32 v[12:13], v[18:19], v[26:27]
	v_pk_add_f32 v[8:9], v[8:9], v[38:39]
	v_pk_add_f32 v[12:13], v[12:13], v[44:45]
	v_pk_add_f32 v[24:25], v[8:9], v[50:51]
	v_pk_add_f32 v[26:27], v[12:13], v[52:53]
	v_pk_add_f32 v[24:25], v[24:25], v[58:59]
	v_pk_add_f32 v[26:27], v[26:27], v[60:61]
	s_waitcnt lgkmcnt(11)
	v_pk_add_f32 v[24:25], v[24:25], v[66:67]
	s_waitcnt lgkmcnt(10)
	v_pk_add_f32 v[26:27], v[26:27], v[68:69]
	s_waitcnt lgkmcnt(7)
	v_pk_add_f32 v[24:25], v[24:25], v[74:75]
	s_waitcnt lgkmcnt(6)
	v_pk_add_f32 v[26:27], v[26:27], v[76:77]
	s_waitcnt lgkmcnt(3)
	v_pk_add_f32 v[24:25], v[24:25], v[82:83]
	s_waitcnt lgkmcnt(2)
	v_pk_add_f32 v[26:27], v[26:27], v[84:85]
	v_lshl_add_u64 v[18:19], v[10:11], 0, s[8:9]
	global_load_dwordx4 v[8:11], v[18:19], off offset:32
	global_load_dwordx4 v[12:15], v[18:19], off offset:96
	s_waitcnt vmcnt(2)
	v_pk_fma_f32 v[2:3], v[26:27], v[6:7], v[2:3]
	v_pk_fma_f32 v[0:1], v[24:25], v[4:5], v[0:1]
	global_store_dwordx4 v[90:91], v[0:3], off
	global_load_dwordx4 v[0:3], v[16:17], off offset:32
	v_pk_add_f32 v[4:5], v[20:21], v[28:29]
	v_pk_add_f32 v[6:7], v[22:23], v[30:31]
	v_pk_add_f32 v[4:5], v[4:5], v[46:47]
	v_pk_add_f32 v[6:7], v[6:7], v[48:49]
	v_pk_add_f32 v[20:21], v[4:5], v[54:55]
	v_pk_add_f32 v[22:23], v[6:7], v[56:57]
	global_load_dwordx4 v[4:7], v[18:19], off offset:64
	v_pk_add_f32 v[18:19], v[20:21], v[62:63]
	v_pk_add_f32 v[20:21], v[22:23], v[64:65]
	v_pk_add_f32 v[18:19], v[18:19], v[70:71]
	v_pk_add_f32 v[20:21], v[20:21], v[72:73]
	v_pk_add_f32 v[18:19], v[18:19], v[78:79]
	v_pk_add_f32 v[20:21], v[20:21], v[80:81]
	s_waitcnt lgkmcnt(1)
	v_pk_add_f32 v[18:19], v[18:19], v[86:87]
	s_waitcnt lgkmcnt(0)
	v_pk_add_f32 v[20:21], v[20:21], v[88:89]
	s_waitcnt vmcnt(1)
	v_pk_fma_f32 v[0:1], v[18:19], v[8:9], v[0:1]
	v_pk_fma_f32 v[2:3], v[20:21], v[10:11], v[2:3]
	global_store_dwordx4 v[90:91], v[0:3], off offset:32
	global_load_dwordx4 v[0:3], v[16:17], off offset:64
	ds_read2st64_b32 v[8:9], v41 offset0:8 offset1:9
	ds_read2st64_b32 v[10:11], v41 offset0:10 offset1:11
	ds_read2st64_b32 v[18:19], v41 offset0:12 offset1:13
	ds_read2st64_b32 v[20:21], v41 offset0:14 offset1:15
	ds_read2st64_b32 v[22:23], v41 offset0:40 offset1:41
	ds_read2st64_b32 v[24:25], v41 offset0:42 offset1:43
	ds_read2st64_b32 v[26:27], v41 offset0:44 offset1:45
	ds_read2st64_b32 v[28:29], v41 offset0:46 offset1:47
	ds_read2st64_b32 v[30:31], v41 offset0:72 offset1:73
	ds_read2st64_b32 v[38:39], v41 offset0:74 offset1:75
	ds_read2st64_b32 v[44:45], v41 offset0:76 offset1:77
	ds_read2st64_b32 v[46:47], v41 offset0:78 offset1:79
	ds_read2st64_b32 v[48:49], v41 offset0:104 offset1:105
	ds_read2st64_b32 v[50:51], v41 offset0:106 offset1:107
	ds_read2st64_b32 v[52:53], v41 offset0:108 offset1:109
	ds_read2st64_b32 v[54:55], v41 offset0:110 offset1:111
	ds_read2st64_b32 v[56:57], v41 offset0:136 offset1:137
	ds_read2st64_b32 v[58:59], v41 offset0:138 offset1:139
	ds_read2st64_b32 v[60:61], v41 offset0:140 offset1:141
	ds_read2st64_b32 v[62:63], v41 offset0:142 offset1:143
	ds_read2st64_b32 v[64:65], v41 offset0:168 offset1:169
	ds_read2st64_b32 v[66:67], v41 offset0:170 offset1:171
	ds_read2st64_b32 v[68:69], v41 offset0:172 offset1:173
	ds_read2st64_b32 v[70:71], v41 offset0:174 offset1:175
	ds_read2st64_b32 v[72:73], v41 offset0:200 offset1:201
	ds_read2st64_b32 v[74:75], v41 offset0:202 offset1:203
	ds_read2st64_b32 v[76:77], v41 offset0:204 offset1:205
	ds_read2st64_b32 v[78:79], v41 offset0:206 offset1:207
	ds_read2st64_b32 v[80:81], v41 offset0:232 offset1:233
	ds_read2st64_b32 v[82:83], v41 offset0:234 offset1:235
	ds_read2st64_b32 v[84:85], v41 offset0:236 offset1:237
	ds_read2st64_b32 v[86:87], v41 offset0:238 offset1:239
	s_waitcnt lgkmcnt(14)
	v_pk_add_f32 v[8:9], v[8:9], v[22:23]
	v_pk_add_f32 v[10:11], v[10:11], v[24:25]
	v_pk_add_f32 v[8:9], v[8:9], v[30:31]
	v_pk_add_f32 v[10:11], v[10:11], v[38:39]
	v_pk_add_f32 v[8:9], v[8:9], v[48:49]
	v_pk_add_f32 v[10:11], v[10:11], v[50:51]
	v_pk_add_f32 v[8:9], v[8:9], v[56:57]
	v_pk_add_f32 v[10:11], v[10:11], v[58:59]
	s_waitcnt lgkmcnt(11)
	v_pk_add_f32 v[8:9], v[8:9], v[64:65]
	s_waitcnt lgkmcnt(10)
	v_pk_add_f32 v[10:11], v[10:11], v[66:67]
	s_waitcnt lgkmcnt(7)
	v_pk_add_f32 v[8:9], v[8:9], v[72:73]
	s_waitcnt lgkmcnt(6)
	v_pk_add_f32 v[10:11], v[10:11], v[74:75]
	s_waitcnt lgkmcnt(3)
	v_pk_add_f32 v[8:9], v[8:9], v[80:81]
	s_waitcnt lgkmcnt(2)
	v_pk_add_f32 v[10:11], v[10:11], v[82:83]
	s_waitcnt vmcnt(0)
	v_pk_fma_f32 v[0:1], v[8:9], v[4:5], v[0:1]
	v_pk_fma_f32 v[2:3], v[10:11], v[6:7], v[2:3]
	global_store_dwordx4 v[90:91], v[0:3], off offset:64
	global_load_dwordx4 v[0:3], v[16:17], off offset:96
	v_pk_add_f32 v[4:5], v[18:19], v[26:27]
	v_pk_add_f32 v[6:7], v[20:21], v[28:29]
	v_pk_add_f32 v[4:5], v[4:5], v[44:45]
	v_pk_add_f32 v[6:7], v[6:7], v[46:47]
	v_pk_add_f32 v[4:5], v[4:5], v[52:53]
	v_pk_add_f32 v[6:7], v[6:7], v[54:55]
	v_pk_add_f32 v[4:5], v[4:5], v[60:61]
	v_pk_add_f32 v[6:7], v[6:7], v[62:63]
	v_pk_add_f32 v[4:5], v[4:5], v[68:69]
	v_pk_add_f32 v[6:7], v[6:7], v[70:71]
	v_pk_add_f32 v[4:5], v[4:5], v[76:77]
	v_pk_add_f32 v[6:7], v[6:7], v[78:79]
	s_waitcnt lgkmcnt(1)
	v_pk_add_f32 v[4:5], v[4:5], v[84:85]
	s_waitcnt lgkmcnt(0)
	v_pk_add_f32 v[6:7], v[6:7], v[86:87]
	s_waitcnt vmcnt(0)
	v_pk_fma_f32 v[0:1], v[4:5], v[12:13], v[0:1]
	v_pk_fma_f32 v[2:3], v[6:7], v[14:15], v[2:3]
	global_store_dwordx4 v[90:91], v[0:3], off offset:96
	s_branch .LBB0_1717
